# DIFF tile body: exp/rowsum/cvt interleaved into the QK(p1) and PV MFMA gaps (fast path), sequential slow path for near-diagonal tiles, V fragments loaded ks-major
# baseline (speedup 1.0000x reference)
.LBB0_856:
	s_lshl_b32 s6, s7, 15
	s_add_i32 s64, s6, 0
	s_add_i32 s6, s64, s92
	v_add3_u32 v253, s6, v136, v137
	v_add_u32_e32 v252, s64, v138
	ds_read_b128 v[186:189], v253
	ds_read_b128 v[190:193], v253 offset:512
	ds_read_b128 v[194:197], v253 offset:2048
	ds_read_b128 v[198:201], v253 offset:2560
	v_add3_u32 v252, v252, v132, v139
	ds_read_b128 v[202:205], v253 offset:4096
	ds_read_b128 v[206:209], v253 offset:4608
	ds_read_b128 v[210:213], v253 offset:6144
	ds_read_b128 v[214:217], v253 offset:6656
	ds_read_b64_tr_b16 v[236:237], v252 offset:18432
	ds_read_b64_tr_b16 v[238:239], v252 offset:18944
	ds_read_b64_tr_b16 v[240:241], v252 offset:19456
	ds_read_b64_tr_b16 v[242:243], v252 offset:19968
	ds_read_b64_tr_b16 v[244:245], v252 offset:22528
	ds_read_b64_tr_b16 v[246:247], v252 offset:23040
	ds_read_b64_tr_b16 v[248:249], v252 offset:23552
	ds_read_b64_tr_b16 v[250:251], v252 offset:24064
	v_add_u32_e32 v0, 59, v140
	s_add_i32 s6, s50, 0xb0
	s_cmp_le_i32 s6, s53
	s_cbranch_scc0 .Ld_slow
	s_waitcnt lgkmcnt(14)
	v_mfma_f32_32x32x16_bf16 v[82:97], v[186:189], v[114:117], v[66:81]
	s_waitcnt lgkmcnt(13)
	v_mfma_f32_32x32x16_bf16 v[82:97], v[194:197], v[118:121], v[82:97]
	s_waitcnt lgkmcnt(11)
	v_mfma_f32_32x32x16_bf16 v[82:97], v[202:205], v[122:125], v[82:97]
	s_waitcnt lgkmcnt(9)
	v_mfma_f32_32x32x16_bf16 v[82:97], v[210:213], v[126:129], v[82:97]
	ds_read_b64_tr_b16 v[186:187], v252 offset:16384
	ds_read_b64_tr_b16 v[188:189], v252 offset:16896
	ds_read_b64_tr_b16 v[194:195], v252 offset:17408
	ds_read_b64_tr_b16 v[196:197], v252 offset:17920
	ds_read_b64_tr_b16 v[202:203], v252 offset:20480
	ds_read_b64_tr_b16 v[204:205], v252 offset:20992
	ds_read_b64_tr_b16 v[210:211], v252 offset:21504
	ds_read_b64_tr_b16 v[212:213], v252 offset:22016
	s_nop 3
	v_exp_f32_e32 v82, v82
	v_exp_f32_e32 v83, v83
	v_exp_f32_e32 v84, v84
	v_mfma_f32_32x32x16_bf16 v[98:113], v[190:193], v[114:117], v[66:81]
	v_exp_f32_e32 v85, v85
	v_exp_f32_e32 v86, v86
	v_exp_f32_e32 v87, v87
	v_exp_f32_e32 v88, v88
	v_mfma_f32_32x32x16_bf16 v[98:113], v[198:201], v[118:121], v[98:113]
	v_exp_f32_e32 v89, v89
	v_exp_f32_e32 v90, v90
	v_exp_f32_e32 v91, v91
	v_exp_f32_e32 v92, v92
	v_mfma_f32_32x32x16_bf16 v[98:113], v[206:209], v[122:125], v[98:113]
	v_exp_f32_e32 v93, v93
	v_exp_f32_e32 v144, v94
	v_exp_f32_e32 v145, v95
	v_exp_f32_e32 v146, v96
	s_waitcnt lgkmcnt(14)
	v_mfma_f32_32x32x16_bf16 v[98:113], v[214:217], v[126:129], v[98:113]
	v_exp_f32_e32 v147, v97
	ds_read_b64_tr_b16 v[190:191], v252 offset:24576
	ds_read_b64_tr_b16 v[192:193], v252 offset:25088
	ds_read_b64_tr_b16 v[198:199], v252 offset:25600
	ds_read_b64_tr_b16 v[200:201], v252 offset:26112
	ds_read_b64_tr_b16 v[206:207], v252 offset:28672
	ds_read_b64_tr_b16 v[208:209], v252 offset:29184
	ds_read_b64_tr_b16 v[214:215], v252 offset:29696
	ds_read_b64_tr_b16 v[216:217], v252 offset:30208
	s_branch .Ld_join
.Ld_slow:
	s_waitcnt lgkmcnt(14)
	v_mfma_f32_32x32x16_bf16 v[82:97], v[186:189], v[114:117], v[66:81]
	s_waitcnt lgkmcnt(14)
	v_mfma_f32_32x32x16_bf16 v[98:113], v[190:193], v[114:117], v[66:81]
	s_waitcnt lgkmcnt(13)
	v_mfma_f32_32x32x16_bf16 v[82:97], v[194:197], v[118:121], v[82:97]
	s_waitcnt lgkmcnt(12)
	v_mfma_f32_32x32x16_bf16 v[98:113], v[198:201], v[118:121], v[98:113]
	s_waitcnt lgkmcnt(11)
	v_mfma_f32_32x32x16_bf16 v[82:97], v[202:205], v[122:125], v[82:97]
	s_waitcnt lgkmcnt(10)
	v_mfma_f32_32x32x16_bf16 v[98:113], v[206:209], v[122:125], v[98:113]
	s_waitcnt lgkmcnt(9)
	v_mfma_f32_32x32x16_bf16 v[82:97], v[210:213], v[126:129], v[82:97]
	s_waitcnt lgkmcnt(8)
	v_mfma_f32_32x32x16_bf16 v[98:113], v[214:217], v[126:129], v[98:113]
	ds_read_b64_tr_b16 v[186:187], v252 offset:16384
	ds_read_b64_tr_b16 v[188:189], v252 offset:16896
	ds_read_b64_tr_b16 v[194:195], v252 offset:17408
	ds_read_b64_tr_b16 v[196:197], v252 offset:17920
	ds_read_b64_tr_b16 v[202:203], v252 offset:20480
	ds_read_b64_tr_b16 v[204:205], v252 offset:20992
	ds_read_b64_tr_b16 v[210:211], v252 offset:21504
	ds_read_b64_tr_b16 v[212:213], v252 offset:22016
	ds_read_b64_tr_b16 v[190:191], v252 offset:24576
	ds_read_b64_tr_b16 v[192:193], v252 offset:25088
	ds_read_b64_tr_b16 v[198:199], v252 offset:25600
	ds_read_b64_tr_b16 v[200:201], v252 offset:26112
	ds_read_b64_tr_b16 v[206:207], v252 offset:28672
	ds_read_b64_tr_b16 v[208:209], v252 offset:29184
	ds_read_b64_tr_b16 v[214:215], v252 offset:29696
	ds_read_b64_tr_b16 v[216:217], v252 offset:30208
	v_add_u32_e32 v144, 58, v140
	v_med3_i32 v144, v144, 0, v234
	v_lshl_add_u32 v145, v144, 2, s73
	v_add_u32_e32 v144, 57, v140
	v_med3_i32 v144, v144, 0, v234
	v_add_u32_e32 v152, 42, v140
	v_lshl_add_u32 v146, v144, 2, s73
	v_add_u32_e32 v144, 56, v140
	v_med3_i32 v152, v152, 0, v234
	v_med3_i32 v144, v144, 0, v234
	v_lshl_add_u32 v153, v152, 2, s73
	v_add_u32_e32 v152, 41, v140
	v_lshl_add_u32 v147, v144, 2, s73
	v_add_u32_e32 v144, 51, v140
	v_med3_i32 v152, v152, 0, v234
	v_add_u32_e32 v160, 26, v140
	v_med3_i32 v144, v144, 0, v234
	v_lshl_add_u32 v154, v152, 2, s73
	v_add_u32_e32 v152, 40, v140
	v_med3_i32 v160, v160, 0, v234
	v_lshl_add_u32 v148, v144, 2, s73
	v_add_u32_e32 v144, 50, v140
	v_med3_i32 v152, v152, 0, v234
	v_lshl_add_u32 v161, v160, 2, s73
	v_add_u32_e32 v160, 25, v140
	v_med3_i32 v144, v144, 0, v234
	v_lshl_add_u32 v155, v152, 2, s73
	v_add_u32_e32 v152, 35, v140
	v_med3_i32 v160, v160, 0, v234
	v_lshl_add_u32 v149, v144, 2, s73
	v_add_u32_e32 v144, 49, v140
	v_med3_i32 v152, v152, 0, v234
	v_lshl_add_u32 v162, v160, 2, s73
	v_add_u32_e32 v160, 24, v140
	v_add_u32_e32 v168, 10, v140
	v_med3_i32 v144, v144, 0, v234
	v_lshl_add_u32 v156, v152, 2, s73
	v_add_u32_e32 v152, 34, v140
	v_med3_i32 v160, v160, 0, v234
	v_med3_i32 v168, v168, 0, v234
	v_lshl_add_u32 v150, v144, 2, s73
	v_add_u32_e32 v144, 48, v140
	v_med3_i32 v152, v152, 0, v234
	v_lshl_add_u32 v163, v160, 2, s73
	v_add_u32_e32 v160, 19, v140
	v_lshl_add_u32 v169, v168, 2, s73
	v_add_u32_e32 v168, 9, v140
	v_med3_i32 v143, v0, 0, v234
	v_med3_i32 v144, v144, 0, v234
	v_lshl_add_u32 v157, v152, 2, s73
	v_add_u32_e32 v152, 33, v140
	v_med3_i32 v160, v160, 0, v234
	v_med3_i32 v168, v168, 0, v234
	v_lshl_add_u32 v143, v143, 2, s73
	v_lshl_add_u32 v151, v144, 2, s73
	v_med3_i32 v152, v152, 0, v234
	v_lshl_add_u32 v164, v160, 2, s73
	v_add_u32_e32 v160, 18, v140
	v_lshl_add_u32 v180, v168, 2, s73
	v_add_u32_e32 v168, 8, v140
	ds_read_b32 v144, v143
	ds_read_b32 v145, v145
	ds_read_b32 v146, v146
	ds_read_b32 v147, v147
	ds_read_b32 v148, v148
	ds_read_b32 v149, v149
	ds_read_b32 v150, v150
	ds_read_b32 v151, v151
	v_add_u32_e32 v143, 43, v140
	v_lshl_add_u32 v158, v152, 2, s73
	v_add_u32_e32 v152, 32, v140
	v_med3_i32 v160, v160, 0, v234
	v_med3_i32 v168, v168, 0, v234
	v_med3_i32 v143, v143, 0, v234
	v_med3_i32 v152, v152, 0, v234
	v_lshl_add_u32 v165, v160, 2, s73
	v_add_u32_e32 v160, 17, v140
	v_lshl_add_u32 v181, v168, 2, s73
	v_add_u32_e32 v168, 3, v140
	v_lshl_add_u32 v143, v143, 2, s73
	v_lshl_add_u32 v159, v152, 2, s73
	v_med3_i32 v160, v160, 0, v234
	v_med3_i32 v168, v168, 0, v234
	ds_read_b32 v152, v143
	ds_read_b32 v153, v153
	ds_read_b32 v154, v154
	ds_read_b32 v155, v155
	ds_read_b32 v156, v156
	ds_read_b32 v157, v157
	ds_read_b32 v158, v158
	ds_read_b32 v159, v159
	v_add_u32_e32 v143, 27, v140
	v_lshl_add_u32 v166, v160, 2, s73
	v_add_u32_e32 v160, 16, v140
	v_lshl_add_u32 v182, v168, 2, s73
	v_add_u32_e32 v168, 2, v140
	v_med3_i32 v143, v143, 0, v234
	v_med3_i32 v160, v160, 0, v234
	v_med3_i32 v168, v168, 0, v234
	v_lshl_add_u32 v143, v143, 2, s73
	v_lshl_add_u32 v167, v160, 2, s73
	v_lshl_add_u32 v183, v168, 2, s73
	v_add_u32_e32 v168, 1, v140
	ds_read_b32 v160, v143
	ds_read_b32 v161, v161
	ds_read_b32 v162, v162
	ds_read_b32 v163, v163
	ds_read_b32 v164, v164
	ds_read_b32 v165, v165
	ds_read_b32 v166, v166
	ds_read_b32 v167, v167
	v_add_u32_e32 v143, 11, v140
	v_med3_i32 v168, v168, 0, v234
	v_med3_i32 v143, v143, 0, v234
	v_lshl_add_u32 v184, v168, 2, s73
	v_med3_i32 v168, v140, 0, v234
	v_lshl_add_u32 v143, v143, 2, s73
	v_lshl_add_u32 v185, v168, 2, s73
	ds_read_b32 v168, v143
	ds_read_b32 v169, v169
	ds_read_b32 v180, v180
	ds_read_b32 v181, v181
	ds_read_b32 v182, v182
	ds_read_b32 v183, v183
	ds_read_b32 v184, v184
	ds_read_b32 v185, v185
	s_waitcnt lgkmcnt(0)
	v_pk_add_f32 v[96:97], v[96:97], v[158:159]
	v_pk_add_f32 v[94:95], v[94:95], v[156:157]
	v_pk_add_f32 v[92:93], v[92:93], v[154:155]
	v_pk_add_f32 v[90:91], v[90:91], v[152:153]
	v_pk_add_f32 v[88:89], v[88:89], v[150:151]
	v_pk_add_f32 v[86:87], v[86:87], v[148:149]
	v_pk_add_f32 v[84:85], v[84:85], v[146:147]
	v_pk_add_f32 v[82:83], v[82:83], v[144:145]
	v_pk_add_f32 v[112:113], v[112:113], v[184:185]
	v_pk_add_f32 v[110:111], v[110:111], v[182:183]
	v_pk_add_f32 v[108:109], v[108:109], v[180:181]
	v_pk_add_f32 v[106:107], v[106:107], v[168:169]
	v_pk_add_f32 v[104:105], v[104:105], v[166:167]
	v_pk_add_f32 v[102:103], v[102:103], v[164:165]
	v_pk_add_f32 v[100:101], v[100:101], v[162:163]
	v_pk_add_f32 v[98:99], v[98:99], v[160:161]

.LBB0_860:
	s_nop 1
	v_exp_f32_e32 v82, v82
	v_exp_f32_e32 v83, v83
	v_exp_f32_e32 v84, v84
	v_exp_f32_e32 v85, v85
	v_exp_f32_e32 v86, v86
	v_exp_f32_e32 v87, v87
	v_exp_f32_e32 v88, v88
	v_exp_f32_e32 v89, v89
	v_exp_f32_e32 v90, v90
	v_exp_f32_e32 v91, v91
	v_exp_f32_e32 v92, v92
	v_exp_f32_e32 v93, v93
	v_exp_f32_e32 v144, v94
	v_exp_f32_e32 v145, v95
	v_exp_f32_e32 v146, v96
	v_exp_f32_e32 v147, v97
.Ld_join:
	v_cvt_pk_bf16_f32 v162, v82, v83
	v_cvt_pk_bf16_f32 v163, v84, v85
	v_cvt_pk_bf16_f32 v164, v86, v87
	v_cvt_pk_bf16_f32 v165, v88, v89
	v_cvt_pk_bf16_f32 v166, v90, v91
	v_cvt_pk_bf16_f32 v167, v92, v93
	v_cvt_pk_bf16_f32 v168, v144, v145
	v_cvt_pk_bf16_f32 v169, v146, v147
	s_waitcnt lgkmcnt(0)
	v_mfma_f32_32x32x16_bf16 v[50:65], v[162:165], v[186:189], v[50:65]
	v_exp_f32_e32 v98, v98
	v_exp_f32_e32 v99, v99
	v_exp_f32_e32 v100, v100
	v_mfma_f32_32x32x16_bf16 v[50:65], v[166:169], v[194:197], v[50:65]
	v_exp_f32_e32 v101, v101
	v_exp_f32_e32 v102, v102
	v_exp_f32_e32 v103, v103
	v_mfma_f32_32x32x16_bf16 v[34:49], v[162:165], v[202:205], v[34:49]
	v_exp_f32_e32 v104, v104
	v_exp_f32_e32 v105, v105
	v_exp_f32_e32 v106, v106
	v_mfma_f32_32x32x16_bf16 v[34:49], v[166:169], v[210:213], v[34:49]
	v_exp_f32_e32 v107, v107
	v_exp_f32_e32 v108, v108
	v_exp_f32_e32 v109, v109
	ds_read_b64_tr_b16 v[186:187], v252 offset:26624
	ds_read_b64_tr_b16 v[188:189], v252 offset:27136
	ds_read_b64_tr_b16 v[194:195], v252 offset:27648
	ds_read_b64_tr_b16 v[196:197], v252 offset:28160
	v_mfma_f32_32x32x16_bf16 v[18:33], v[162:165], v[190:193], v[18:33]
	v_exp_f32_e32 v110, v110
	v_exp_f32_e32 v111, v111
	v_exp_f32_e32 v112, v112
	ds_read_b64_tr_b16 v[202:203], v252 offset:30720
	ds_read_b64_tr_b16 v[204:205], v252 offset:31232
	ds_read_b64_tr_b16 v[210:211], v252 offset:31744
	ds_read_b64_tr_b16 v[212:213], v252 offset:32256
	v_mfma_f32_32x32x16_bf16 v[18:33], v[166:169], v[198:201], v[18:33]
	v_exp_f32_e32 v113, v113
	v_pk_add_f32 v[156:157], v[84:85], v[100:101]
	v_pk_add_f32 v[158:159], v[82:83], v[98:99]
	v_pk_add_f32 v[152:153], v[88:89], v[104:105]
	v_pk_add_f32 v[154:155], v[86:87], v[102:103]
	v_mfma_f32_32x32x16_bf16 v[2:17], v[162:165], v[206:209], v[2:17]
	v_cvt_pk_bf16_f32 v86, v98, v99
	v_cvt_pk_bf16_f32 v87, v100, v101
	v_cvt_pk_bf16_f32 v88, v102, v103
	v_cvt_pk_bf16_f32 v89, v104, v105
	v_cvt_pk_bf16_f32 v82, v106, v107
	v_cvt_pk_bf16_f32 v83, v108, v109
	v_mfma_f32_32x32x16_bf16 v[2:17], v[166:169], v[214:217], v[2:17]
	v_cvt_pk_bf16_f32 v84, v110, v111
	v_cvt_pk_bf16_f32 v85, v112, v113
	v_pk_mov_b32 v[160:161], v[158:159], v[156:157] op_sel:[1,0]
	v_mov_b32_e32 v159, v157
	v_pk_add_f32 v[156:157], v[160:161], v[158:159]
	v_pk_mov_b32 v[158:159], v[154:155], v[152:153] op_sel:[1,0]
	v_mfma_f32_32x32x16_bf16 v[50:65], v[86:89], v[236:239], v[50:65]
	v_mov_b32_e32 v155, v153
	v_pk_add_f32 v[152:153], v[158:159], v[154:155]
	v_pk_add_f32 v[94:95], v[146:147], v[112:113]
	v_mfma_f32_32x32x16_bf16 v[50:65], v[82:85], v[240:243], v[50:65]
	v_pk_add_f32 v[96:97], v[144:145], v[110:111]
	v_pk_add_f32 v[148:149], v[92:93], v[108:109]
	v_pk_add_f32 v[150:151], v[90:91], v[106:107]
	v_mfma_f32_32x32x16_bf16 v[34:49], v[86:89], v[244:247], v[34:49]
	v_pk_add_f32 v[156:157], v[156:157], v[156:157] op_sel_hi:[0,1]
	v_pk_add_f32 v[152:153], v[152:153], v[152:153] op_sel_hi:[0,1]
	v_add_f32_e32 v151, v150, v151
	v_mfma_f32_32x32x16_bf16 v[34:49], v[82:85], v[248:251], v[34:49]
	v_add_f32_e32 v149, v148, v149
	v_mov_b32_e32 v150, v96
	v_mov_b32_e32 v148, v97
	s_waitcnt lgkmcnt(0)
	v_mfma_f32_32x32x16_bf16 v[18:33], v[86:89], v[186:189], v[18:33]
	v_mov_b32_e32 v156, v94
	v_mov_b32_e32 v152, v95
	v_pk_add_f32 v[96:97], v[150:151], v[148:149]
	v_mfma_f32_32x32x16_bf16 v[18:33], v[82:85], v[194:197], v[18:33]
	v_pk_add_f32 v[94:95], v[156:157], v[152:153]
	v_pk_add_f32 v[94:95], v[96:97], v[94:95]
	v_add_f32_e32 v0, v94, v95
	v_add_f32_e32 v135, v135, v0
	v_mfma_f32_32x32x16_bf16 v[2:17], v[86:89], v[202:205], v[2:17]
	v_mfma_f32_32x32x16_bf16 v[2:17], v[82:85], v[210:213], v[2:17]
	s_add_i32 s50, s50, 64
	s_cmp_eq_u32 s93, s3
	v_subrev_u32_e32 v140, 64, v140
	s_cbranch_scc1 .LBB0_865
